# same as previous with fast-path guard bound<=32 (exp2 argument never below -64)
# speedup vs baseline: 1.0242x; 1.0032x over previous
; DI void e1_chunk(const Params& p, int layer, int chunk) {
;     ...
;     const float* gain = (j < 4 ? p.b_q_gain : p.b_k_gain) + layer * 64;
;     const float post = j < 4 ? QSCALE64 : 1.f;
; template <int MODE>
; DI void attn_tile(const Params& p, int layer, int tile, char* smem) {
;     ...
;   f32x16 o0, o1, negm;
; #pragma unroll
;   for (int i = 0; i < 16; ++i) { o0[i] = 0.f; o1[i] = 0.f; negm[i] = 0.f; }
;   float mref = 0.f, lsum = 0.f;
;   bool started = false;
;   int qr = 0, qc = 0, cs = 0, rs = 0;
;   if (MODE == 2) { qr = qpos >> 6; qc = qpos & 63; cs = qc - 8; cs = cs < 0 ? 0 : (cs > 48 ? 48 : cs); rs = qr - 4; rs = rs < 0 ? 0 : (rs > 56 ? 56 : rs); }
;   const int i16 = lane & 15, qq = i16 >> 2, pp4 = i16 & 3, g16 = (lane >> 4) & 1;
.LBB0_131:
	v_readlane_b32 s0, v253, 38
	v_readlane_b32 s1, v253, 39
	v_readlane_b32 s4, v253, 40
	v_readlane_b32 s5, v253, 41
	v_readlane_b32 s6, v255, 46
	s_lshl_b32 s6, s6, 8
	s_add_u32 s0, s0, s6
	s_addc_u32 s1, s1, 0
	s_add_u32 s4, s4, s6
	s_addc_u32 s5, s5, 0
	v_lshlrev_b32_e32 v2, 2, v196
	global_load_dword v3, v2, s[0:1]
	global_load_dword v4, v2, s[4:5]
	s_waitcnt vmcnt(0)
	v_and_b32_e32 v3, 0x7fffffff, v3
	v_and_b32_e32 v4, 0x7fffffff, v4
	v_lshlrev_b32_e32 v5, 2, v252
	ds_bpermute_b32 v6, v5, v3
	ds_bpermute_b32 v7, v5, v4
	s_waitcnt lgkmcnt(0)
	v_max_f32_e32 v3, v3, v6
	v_max_f32_e32 v4, v4, v7
	v_lshlrev_b32_e32 v5, 2, v195
	ds_bpermute_b32 v6, v5, v3
	ds_bpermute_b32 v7, v5, v4
	s_waitcnt lgkmcnt(0)
	v_max_f32_e32 v3, v3, v6
	v_max_f32_e32 v4, v4, v7
	v_lshlrev_b32_e32 v5, 2, v198
	ds_bpermute_b32 v6, v5, v3
	ds_bpermute_b32 v7, v5, v4
	s_waitcnt lgkmcnt(0)
	v_max_f32_e32 v3, v3, v6
	v_max_f32_e32 v4, v4, v7
	v_lshlrev_b32_e32 v5, 2, v199
	ds_bpermute_b32 v6, v5, v3
	ds_bpermute_b32 v7, v5, v4
	s_waitcnt lgkmcnt(0)
	v_max_f32_e32 v3, v3, v6
	v_max_f32_e32 v4, v4, v7
	v_lshlrev_b32_e32 v5, 2, v200
	ds_bpermute_b32 v6, v5, v3
	ds_bpermute_b32 v7, v5, v4
	s_waitcnt lgkmcnt(0)
	v_max_f32_e32 v3, v3, v6
	v_max_f32_e32 v4, v4, v7
	v_lshlrev_b32_e32 v5, 2, v201
	ds_bpermute_b32 v6, v5, v3
	ds_bpermute_b32 v7, v5, v4
	s_waitcnt lgkmcnt(0)
	v_max_f32_e32 v3, v3, v6
	v_max_f32_e32 v4, v4, v7
	v_mul_f32_e32 v3, v3, v4
	v_mul_f32_e32 v3, 0xc13c0000, v3
	s_nop 1
	v_readfirstlane_b32 s84, v3
	s_nop 3
	s_cmp_le_u32 s84, 0xc2000000
	s_cselect_b32 s85, 1, 0
	s_cmp_ge_u32 s84, 0x80000000
	s_cselect_b32 s85, s85, 0
	v_readlane_b32 s26, v254, 15
	s_mov_b32 s16, 0
	v_readlane_b32 s20, v254, 9
	v_readlane_b32 s21, v254, 10
	v_readlane_b32 s22, v254, 11
	v_readlane_b32 s23, v254, 12
	v_readlane_b32 s24, v254, 13
	v_readlane_b32 s25, v254, 14
	v_readlane_b32 s27, v254, 16
	s_branch .LBB0_134
